# hand-pipelined diff-attention inner loop (exp/cvt interleaved with MFMAs, no sinit copies); same numerics
# speedup vs baseline: 1.0172x; 1.0172x over previous
.LBB0_544:
	s_cmp_lg_u32 s14, 0
	s_cbranch_scc1 .Ldf_loop
	s_cmpk_lg_i32 s14, 0x7f
	s_cselect_b64 s[34:35], -1, 0
	s_cmpk_eq_i32 s14, 0x7f
	s_cbranch_scc1 .LBB0_546
	v_lshl_add_u64 v[80:81], v[148:149], 0, v[200:201]
	v_add_co_u32_e32 v80, vcc, 0xad40000, v80
	v_lshl_add_u64 v[82:83], v[150:151], 0, v[200:201]
	s_nop 0
	v_addc_co_u32_e32 v81, vcc, 0, v81, vcc
	global_load_dwordx4 v[112:115], v[80:81], off offset:1024
	global_load_dwordx4 v[116:119], v[80:81], off offset:1152
	v_add_co_u32_e32 v80, vcc, 0x12d00000, v82
	s_nop 1
	v_addc_co_u32_e32 v81, vcc, 0, v83, vcc
	v_add_co_u32_e32 v82, vcc, 0x12e00000, v82
	s_nop 1
	v_addc_co_u32_e32 v83, vcc, 0, v83, vcc
	global_load_dwordx4 v[136:139], v[80:81], off offset:128
	global_load_dwordx4 v[140:143], v[82:83], off offset:128

.Ldf_loop:
	s_bitcmp1_b32 s14, 0
	s_cselect_b32 s37, 0x9000, 0
	s_mul_i32 s12, s36, 0x2400
	s_add_i32 s12, s37, s12
	v_add3_u32 v246, s12, v144, v163
	v_add3_u32 v247, s37, v161, v144
	ds_read_b128 v[166:169], v246
	ds_read_b128 v[170:173], v246 offset:32
	ds_read_b128 v[174:177], v246 offset:64
	ds_read_b128 v[178:181], v246 offset:96
	ds_read_b128 v[182:185], v246 offset:4608
	ds_read_b128 v[186:189], v246 offset:4640
	ds_read_b128 v[190:193], v246 offset:4672
	ds_read_b128 v[194:197], v246 offset:4704
	s_cmpk_eq_i32 s14, 0x7f
	s_cbranch_scc1 .Ldf_noload
	v_lshl_add_u64 v[248:249], v[148:149], 0, v[200:201]
	v_add_co_u32_e32 v248, vcc, 0xad40000, v248
	v_lshl_add_u64 v[250:251], v[150:151], 0, v[200:201]
	s_nop 0
	v_addc_co_u32_e32 v249, vcc, 0, v249, vcc
	global_load_dwordx4 v[112:115], v[248:249], off offset:1024
	global_load_dwordx4 v[116:119], v[248:249], off offset:1152
	v_add_co_u32_e32 v248, vcc, 0x12d00000, v250
	s_nop 1
	v_addc_co_u32_e32 v249, vcc, 0, v251, vcc
	v_add_co_u32_e32 v250, vcc, 0x12e00000, v250
	s_nop 1
	v_addc_co_u32_e32 v251, vcc, 0, v251, vcc
	global_load_dwordx4 v[136:139], v[248:249], off offset:128
	global_load_dwordx4 v[140:143], v[250:251], off offset:128
.Ldf_noload:
	s_waitcnt lgkmcnt(7)
	v_mfma_f32_32x32x16_bf16 v[96:111], v[166:169], v[120:123], v[64:79]
	s_waitcnt lgkmcnt(6)
	v_mfma_f32_32x32x16_bf16 v[96:111], v[170:173], v[124:127], v[96:111]
	s_waitcnt lgkmcnt(5)
	v_mfma_f32_32x32x16_bf16 v[96:111], v[174:177], v[128:131], v[96:111]
	s_waitcnt lgkmcnt(4)
	v_mfma_f32_32x32x16_bf16 v[96:111], v[178:181], v[132:135], v[96:111]
	ds_read_b128 v[202:205], v247 offset:18432
	ds_read_b128 v[206:209], v247 offset:23040
	ds_read_b128 v[210:213], v247 offset:27648
	ds_read_b128 v[214:217], v247 offset:32256
	ds_read_b128 v[218:221], v247 offset:18464
	ds_read_b128 v[222:225], v247 offset:23072
	ds_read_b128 v[226:229], v247 offset:27680
	ds_read_b128 v[152:155], v247 offset:32288
	s_waitcnt lgkmcnt(11)
	v_mfma_f32_32x32x16_bf16 v[80:95], v[182:185], v[120:123], v[64:79]
	s_nop 2
	v_exp_f32_e32 v96, v96
	v_exp_f32_e32 v97, v97
	v_exp_f32_e32 v98, v98
	s_waitcnt lgkmcnt(10)
	v_mfma_f32_32x32x16_bf16 v[80:95], v[186:189], v[124:127], v[80:95]
	v_exp_f32_e32 v99, v99
	v_add_f32_e32 v242, v96, v98
	v_add_f32_e32 v243, v97, v99
	v_exp_f32_e32 v100, v100
	s_waitcnt lgkmcnt(9)
	v_mfma_f32_32x32x16_bf16 v[80:95], v[190:193], v[128:131], v[80:95]
	v_exp_f32_e32 v101, v101
	v_add_f32_e32 v242, v242, v100
	v_add_f32_e32 v243, v243, v101
	v_exp_f32_e32 v102, v102
	s_waitcnt lgkmcnt(8)
	v_mfma_f32_32x32x16_bf16 v[80:95], v[194:197], v[132:135], v[80:95]
	v_exp_f32_e32 v103, v103
	v_add_f32_e32 v242, v242, v102
	v_add_f32_e32 v243, v243, v103
	v_cvt_pk_bf16_f32 v96, v96, v97
	v_cvt_pk_bf16_f32 v97, v98, v99
	v_cvt_pk_bf16_f32 v98, v100, v101
	v_cvt_pk_bf16_f32 v99, v102, v103
	s_nop 1
	s_waitcnt lgkmcnt(7)
	v_mfma_f32_32x32x16_bf16 v[48:63], v[202:205], v[96:99], v[48:63]
	ds_read_b128 v[202:205], v247 offset:18496
	v_exp_f32_e32 v104, v104
	v_exp_f32_e32 v105, v105
	v_add_f32_e32 v242, v242, v104
	v_add_f32_e32 v243, v243, v105
	s_waitcnt lgkmcnt(7)
	v_mfma_f32_32x32x16_bf16 v[32:47], v[206:209], v[96:99], v[32:47]
	ds_read_b128 v[206:209], v247 offset:23104
	v_exp_f32_e32 v106, v106
	v_exp_f32_e32 v107, v107
	v_add_f32_e32 v242, v242, v106
	v_add_f32_e32 v243, v243, v107
	s_waitcnt lgkmcnt(7)
	v_mfma_f32_32x32x16_bf16 v[16:31], v[210:213], v[96:99], v[16:31]
	ds_read_b128 v[210:213], v247 offset:27712
	v_exp_f32_e32 v108, v108
	v_exp_f32_e32 v109, v109
	v_add_f32_e32 v242, v242, v108
	v_add_f32_e32 v243, v243, v109
	s_waitcnt lgkmcnt(7)
	v_mfma_f32_32x32x16_bf16 v[0:15], v[214:217], v[96:99], v[0:15]
	ds_read_b128 v[214:217], v247 offset:32320
	v_exp_f32_e32 v110, v110
	v_exp_f32_e32 v111, v111
	v_add_f32_e32 v242, v242, v110
	v_add_f32_e32 v243, v243, v111
	v_cvt_pk_bf16_f32 v104, v104, v105
	v_cvt_pk_bf16_f32 v105, v106, v107
	v_cvt_pk_bf16_f32 v106, v108, v109
	v_cvt_pk_bf16_f32 v107, v110, v111
	s_nop 0
	s_waitcnt lgkmcnt(7)
	v_mfma_f32_32x32x16_bf16 v[48:63], v[218:221], v[104:107], v[48:63]
	ds_read_b128 v[218:221], v247 offset:18528
	v_exp_f32_e32 v80, v80
	v_exp_f32_e32 v81, v81
	v_exp_f32_e32 v82, v82
	s_waitcnt lgkmcnt(7)
	v_mfma_f32_32x32x16_bf16 v[32:47], v[222:225], v[104:107], v[32:47]
	ds_read_b128 v[222:225], v247 offset:23136
	v_exp_f32_e32 v83, v83
	v_add_f32_e32 v244, v80, v82
	v_add_f32_e32 v245, v81, v83
	v_exp_f32_e32 v84, v84
	s_waitcnt lgkmcnt(7)
	v_mfma_f32_32x32x16_bf16 v[16:31], v[226:229], v[104:107], v[16:31]
	ds_read_b128 v[226:229], v247 offset:27744
	v_exp_f32_e32 v85, v85
	v_add_f32_e32 v244, v244, v84
	v_add_f32_e32 v245, v245, v85
	v_exp_f32_e32 v86, v86
	s_waitcnt lgkmcnt(7)
	v_mfma_f32_32x32x16_bf16 v[0:15], v[152:155], v[104:107], v[0:15]
	ds_read_b128 v[152:155], v247 offset:32352
	v_exp_f32_e32 v87, v87
	v_add_f32_e32 v244, v244, v86
	v_add_f32_e32 v245, v245, v87
	v_cvt_pk_bf16_f32 v80, v80, v81
	v_cvt_pk_bf16_f32 v81, v82, v83
	v_cvt_pk_bf16_f32 v82, v84, v85
	v_cvt_pk_bf16_f32 v83, v86, v87
	s_nop 0
	s_waitcnt lgkmcnt(7)
	v_mfma_f32_32x32x16_bf16 v[48:63], v[202:205], v[80:83], v[48:63]
	v_exp_f32_e32 v88, v88
	v_exp_f32_e32 v89, v89
	v_add_f32_e32 v244, v244, v88
	v_add_f32_e32 v245, v245, v89
	s_waitcnt lgkmcnt(6)
	v_mfma_f32_32x32x16_bf16 v[32:47], v[206:209], v[80:83], v[32:47]
	v_exp_f32_e32 v90, v90
	v_exp_f32_e32 v91, v91
	v_add_f32_e32 v244, v244, v90
	v_add_f32_e32 v245, v245, v91
	s_waitcnt lgkmcnt(5)
	v_mfma_f32_32x32x16_bf16 v[16:31], v[210:213], v[80:83], v[16:31]
	v_exp_f32_e32 v92, v92
	v_exp_f32_e32 v93, v93
	v_add_f32_e32 v244, v244, v92
	v_add_f32_e32 v245, v245, v93
	s_waitcnt lgkmcnt(4)
	v_mfma_f32_32x32x16_bf16 v[0:15], v[214:217], v[80:83], v[0:15]
	v_exp_f32_e32 v94, v94
	v_exp_f32_e32 v95, v95
	v_add_f32_e32 v244, v244, v94
	v_add_f32_e32 v245, v245, v95
	v_cvt_pk_bf16_f32 v88, v88, v89
	v_cvt_pk_bf16_f32 v89, v90, v91
	v_cvt_pk_bf16_f32 v90, v92, v93
	v_cvt_pk_bf16_f32 v91, v94, v95
	s_nop 0
	s_waitcnt lgkmcnt(3)
	v_mfma_f32_32x32x16_bf16 v[48:63], v[218:221], v[88:91], v[48:63]
	v_add_f32_e32 v242, v242, v243
	v_add_f32_e32 v244, v244, v245
	s_waitcnt lgkmcnt(2)
	v_mfma_f32_32x32x16_bf16 v[32:47], v[222:225], v[88:91], v[32:47]
	v_lshl_add_u64 v[148:149], v[148:149], 0, s[28:29]
	v_lshl_add_u64 v[150:151], v[150:151], 0, s[26:27]
	s_waitcnt lgkmcnt(1)
	v_mfma_f32_32x32x16_bf16 v[16:31], v[226:229], v[88:91], v[16:31]
	v_add_f32_e32 v242, v242, v244
	s_waitcnt lgkmcnt(0)
	v_mfma_f32_32x32x16_bf16 v[0:15], v[152:155], v[88:91], v[0:15]
	v_cmp_lt_f32_e32 vcc, s33, v242
	s_cbranch_vccz .Ldf_norescale
	s_nop 15
	ds_bpermute_b32 v156, v230, v242
	s_waitcnt lgkmcnt(0)
	v_add_f32_e32 v156, v156, v242
	v_frexp_exp_i32_f32_e32 v156, v156
	v_max_i32_e32 v156, 1, v156
	v_add_u32_e32 v156, -1, v156
	v_cvt_f32_u32_e32 v156, v156
	v_exp_f32_e64 v157, -v156
	v_add_f32_e32 v165, v165, v156
	v_xor_b32_e32 v64, 0x80000000, v165
	v_mul_f32_e32 v164, v164, v157
	v_mul_f32_e32 v242, v242, v157
	v_mul_f32_e32 v0, v0, v157
	v_mul_f32_e32 v1, v1, v157
	v_mul_f32_e32 v2, v2, v157
	v_mul_f32_e32 v3, v3, v157
	v_mul_f32_e32 v4, v4, v157
	v_mul_f32_e32 v5, v5, v157
	v_mul_f32_e32 v6, v6, v157
	v_mul_f32_e32 v7, v7, v157
	v_mul_f32_e32 v8, v8, v157
	v_mul_f32_e32 v9, v9, v157
	v_mul_f32_e32 v10, v10, v157
	v_mul_f32_e32 v11, v11, v157
	v_mul_f32_e32 v12, v12, v157
	v_mul_f32_e32 v13, v13, v157
	v_mul_f32_e32 v14, v14, v157
	v_mul_f32_e32 v15, v15, v157
	v_mul_f32_e32 v16, v16, v157
	v_mul_f32_e32 v17, v17, v157
	v_mul_f32_e32 v18, v18, v157
	v_mul_f32_e32 v19, v19, v157
	v_mul_f32_e32 v20, v20, v157
	v_mul_f32_e32 v21, v21, v157
	v_mul_f32_e32 v22, v22, v157
	v_mul_f32_e32 v23, v23, v157
	v_mul_f32_e32 v24, v24, v157
	v_mul_f32_e32 v25, v25, v157
	v_mul_f32_e32 v26, v26, v157
	v_mul_f32_e32 v27, v27, v157
	v_mul_f32_e32 v28, v28, v157
	v_mul_f32_e32 v29, v29, v157
	v_mul_f32_e32 v30, v30, v157
	v_mul_f32_e32 v31, v31, v157
	v_mul_f32_e32 v32, v32, v157
	v_mul_f32_e32 v33, v33, v157
	v_mul_f32_e32 v34, v34, v157
	v_mul_f32_e32 v35, v35, v157
	v_mul_f32_e32 v36, v36, v157
	v_mul_f32_e32 v37, v37, v157
	v_mul_f32_e32 v38, v38, v157
	v_mul_f32_e32 v39, v39, v157
	v_mul_f32_e32 v40, v40, v157
	v_mul_f32_e32 v41, v41, v157
	v_mul_f32_e32 v42, v42, v157
	v_mul_f32_e32 v43, v43, v157
	v_mul_f32_e32 v44, v44, v157
	v_mul_f32_e32 v45, v45, v157
	v_mul_f32_e32 v46, v46, v157
	v_mul_f32_e32 v47, v47, v157
	v_mul_f32_e32 v48, v48, v157
	v_mul_f32_e32 v49, v49, v157
	v_mul_f32_e32 v50, v50, v157
	v_mul_f32_e32 v51, v51, v157
	v_mul_f32_e32 v52, v52, v157
	v_mul_f32_e32 v53, v53, v157
	v_mul_f32_e32 v54, v54, v157
	v_mul_f32_e32 v55, v55, v157
	v_mul_f32_e32 v56, v56, v157
	v_mul_f32_e32 v57, v57, v157
	v_mul_f32_e32 v58, v58, v157
	v_mul_f32_e32 v59, v59, v157
	v_mul_f32_e32 v60, v60, v157
	v_mul_f32_e32 v61, v61, v157
	v_mul_f32_e32 v62, v62, v157
	v_mul_f32_e32 v63, v63, v157
	v_mov_b32_e32 v65, v64
	v_mov_b32_e32 v66, v64
	v_mov_b32_e32 v67, v64
	v_mov_b32_e32 v68, v64
	v_mov_b32_e32 v69, v64
	v_mov_b32_e32 v70, v64
	v_mov_b32_e32 v71, v64
	v_mov_b32_e32 v72, v64
	v_mov_b32_e32 v73, v64
	v_mov_b32_e32 v74, v64
	v_mov_b32_e32 v75, v64
	v_mov_b32_e32 v76, v64
	v_mov_b32_e32 v77, v64
	v_mov_b32_e32 v78, v64
	v_mov_b32_e32 v79, v64
.Ldf_norescale:
	v_add_f32_e32 v164, v164, v242
	s_add_i32 s14, s14, 1
	s_cmpk_eq_i32 s14, 0x80
	s_cbranch_scc1 .Ldf_last
	s_bitcmp1_b32 s14, 0
	s_cselect_b32 s12, 0x9000, 0
	v_add_u32_e32 v156, s12, v162
	s_waitcnt vmcnt(3)
	ds_write_b128 v156, v[112:115]
	s_waitcnt vmcnt(2)
	ds_write_b128 v156, v[116:119] offset:9216
	s_waitcnt vmcnt(1)
	ds_write_b128 v156, v[136:139] offset:18432
	s_waitcnt vmcnt(0)
	ds_write_b128 v156, v[140:143] offset:27648
	s_waitcnt lgkmcnt(0)
	s_barrier
	s_branch .Ldf_loop
.Ldf_last:
	s_nop 7
	s_waitcnt lgkmcnt(0)
	s_barrier
	s_branch .LBB0_552
